# rec_pass1 last segment: the LIGHT wave of each SIMD pair (fewer key blocks) runs at s_setprio 2; on top of the static GEMM-phase priority
# baseline (speedup 1.0000x reference)
.LBB0_196:
	s_or_b64 exec, exec, s[2:3]
	v_mul_u32_u24_e32 v4, 0x84, v114
	v_add3_u32 v6, v105, v104, v4
	ds_read2_b32 v[228:229], v6 offset1:33
	ds_read2_b32 v[230:231], v6 offset0:66 offset1:99
	ds_read2_b32 v[232:233], v6 offset0:132 offset1:165
	ds_read2_b32 v[234:235], v6 offset0:198 offset1:231
	s_movk_i32 s2, 0x90
	v_bfe_u32 v7, v111, 5, 3
	v_lshlrev_b32_e32 v8, 4, v7
	v_mul_u32_u24_e32 v7, 0x420, v7
	v_lshlrev_b32_e32 v15, 3, v112
	s_waitcnt lgkmcnt(0)
	v_pk_add_f32 v[228:229], v[106:107], v[228:229] op_sel_hi:[0,1]
	v_pk_add_f32 v[230:231], v[106:107], v[230:231] op_sel_hi:[0,1]
	v_pk_add_f32 v[232:233], v[106:107], v[232:233] op_sel_hi:[0,1]
	v_pk_add_f32 v[234:235], v[106:107], v[234:235] op_sel_hi:[0,1]
	ds_write2_b32 v6, v228, v229 offset1:33
	ds_write2_b32 v6, v230, v231 offset0:66 offset1:99
	ds_write2_b32 v6, v232, v233 offset0:132 offset1:165
	ds_write2_b32 v6, v234, v235 offset0:198 offset1:231
	v_and_b32_e32 v5, 31, v111
	v_lshlrev_b32_e32 v6, 2, v5
	v_add_u32_e32 v4, v105, v6
	s_waitcnt lgkmcnt(0)
	s_barrier
	ds_read_b32 v4, v4 offset:8316
	v_mad_u32_u24 v5, v5, s2, v105
	s_mov_b32 s2, 0xac00
	v_add3_u32 v5, v5, v8, s2
	v_add3_u32 v6, v105, v7, v6
	v_add_u32_e32 v199, 0x210, v6
	v_add_u32_e32 v200, 0x4400, v6
	v_add_u32_e32 v201, 0x4610, v6
	ds_read2_b32 v[236:237], v200 offset1:33
	ds_read2_b32 v[238:239], v6 offset1:33
	ds_read2_b32 v[240:241], v200 offset0:66 offset1:99
	ds_read2_b32 v[242:243], v6 offset0:66 offset1:99
	ds_read2_b32 v[244:245], v201 offset1:33
	ds_read2_b32 v[246:247], v199 offset1:33
	ds_read2_b32 v[248:249], v201 offset0:66 offset1:99
	ds_read2_b32 v[250:251], v199 offset0:66 offset1:99
	s_waitcnt lgkmcnt(0)
	v_sub_f32_e32 v238, v4, v238
	v_sub_f32_e32 v239, v4, v239
	v_sub_f32_e32 v242, v4, v242
	v_sub_f32_e32 v243, v4, v243
	s_nop 0
	s_nop 0
	s_nop 0
	s_nop 0
	v_exp_f32_e32 v238, v238
	v_exp_f32_e32 v239, v239
	v_exp_f32_e32 v242, v242
	v_exp_f32_e32 v243, v243
	s_nop 0
	v_mul_f32_e32 v238, v236, v238
	v_mul_f32_e32 v239, v237, v239
	v_mul_f32_e32 v242, v240, v242
	v_mul_f32_e32 v243, v241, v243
	v_cvt_pk_bf16_f32 v236, v238, v239
	v_cvt_pk_bf16_f32 v237, v242, v243
	ds_write_b64 v5, v[236:237]
	v_sub_f32_e32 v246, v4, v246
	v_sub_f32_e32 v247, v4, v247
	v_sub_f32_e32 v250, v4, v250
	v_sub_f32_e32 v251, v4, v251
	s_nop 0
	s_nop 0
	s_nop 0
	s_nop 0
	v_exp_f32_e32 v246, v246
	v_exp_f32_e32 v247, v247
	v_exp_f32_e32 v250, v250
	v_exp_f32_e32 v251, v251
	s_nop 0
	v_mul_f32_e32 v246, v244, v246
	v_mul_f32_e32 v247, v245, v247
	v_mul_f32_e32 v250, v248, v250
	v_mul_f32_e32 v251, v249, v251
	v_cvt_pk_bf16_f32 v244, v246, v247
	v_cvt_pk_bf16_f32 v245, v250, v251
	ds_write_b64 v5, v[244:245] offset:8
	v_lshl_add_u32 v8, v15, 1, v105
	s_movk_i32 s2, 0x90
	v_mad_u32_u24 v12, v110, s2, v8
	s_waitcnt lgkmcnt(0)
	s_barrier
	v_readfirstlane_b32 s100, v206
	s_nop 3
	s_lshr_b32 s100, s100, 6
	s_sub_i32 s101, 7, s100
	s_cmp_lt_u32 s100, 4
	s_cselect_b32 s100, s100, s101
	s_cmp_ge_u32 s100, 2
	s_cbranch_scc1 .Llprio_g
	s_setprio 2
.Llprio_g:
	ds_read_b128 v[4:7], v12 offset:34816
	v_mad_u32_u24 v13, v107, s2, v8
	ds_read_b128 v[8:11], v13 offset:44032
	ds_read_b128 v[16:19], v13 offset:46336
	ds_read_b128 v[20:23], v12 offset:34880
	ds_read_b128 v[24:27], v13 offset:46400
	s_waitcnt lgkmcnt(3)
	v_mfma_f32_16x16x32_bf16 v[8:11], v[8:11], v[4:7], 0
	v_ashrrev_i32_e32 v103, 31, v102
	v_readlane_b32 s2, v254, 17
	v_readlane_b32 s3, v254, 18
	s_waitcnt lgkmcnt(2)
	v_mfma_f32_16x16x32_bf16 v[4:7], v[16:19], v[4:7], 0
	ds_read_b128 v[16:19], v13 offset:44096
	v_mov_b32_e32 v13, v177
	v_cmp_lt_u32_sdwa s[4:5], v111, v218 src0_sel:BYTE_0 src1_sel:DWORD
	s_waitcnt lgkmcnt(1)
	v_mfma_f32_16x16x32_bf16 v[4:7], v[24:27], v[20:23], v[4:7]
	v_lshlrev_b32_e32 v24, 2, v112
	s_waitcnt lgkmcnt(0)
	v_mfma_f32_16x16x32_bf16 v[16:19], v[16:19], v[20:23], v[8:11]
	s_nop 2
	v_or_b32_e32 v198, v113, v107
	v_lshl_or_b32 v198, v198, 5, v24
	v_lshlrev_b32_e32 v196, 2, v198
	v_mov_b32_e32 v197, v177
	v_or_b32_e32 v11, v113, v24
	v_lshlrev_b32_e32 v11, 5, v11
	v_lshlrev_b64 v[8:9], 13, v[102:103]
	v_or_b32_e32 v12, v11, v107
	v_lshl_add_u64 v[8:9], s[2:3], 0, v[8:9]
	v_lshl_add_u64 v[196:197], v[8:9], 0, v[196:197]
	v_lshlrev_b32_e32 v12, 2, v12
	v_or_b32_e32 v10, 16, v107
	v_lshl_add_u64 v[12:13], v[8:9], 0, v[12:13]
	global_store_dwordx4 v[196:197], v[16:19], off sc1
	global_store_dwordx4 v[196:197], v[4:7], off offset:64 sc1
	s_nop 1
	v_or_b32_e32 v4, v11, v10
	v_lshlrev_b32_e32 v12, 2, v4
	v_mov_b32_e32 v13, v177
	v_lshl_add_u64 v[8:9], v[8:9], 0, v[12:13]
	s_and_saveexec_b64 s[2:3], s[4:5]
	s_cbranch_execz .LBB0_200
	v_lshlrev_b32_sdwa v4, v213, v111 dst_sel:DWORD dst_unused:UNUSED_PAD src0_sel:DWORD src1_sel:BYTE_0
	v_add_u32_e32 v5, v105, v4
	ds_read_b32 v5, v5 offset:8316
	v_readlane_b32 s4, v254, 19
	v_lshlrev_b64 v[6:7], 7, v[102:103]
	v_readlane_b32 s5, v254, 20
	s_waitcnt lgkmcnt(0)
	s_nop 0
	v_exp_f32_e32 v8, v5
	v_lshl_add_u64 v[6:7], s[4:5], 0, v[6:7]
	v_mov_b32_e32 v5, v177
	v_lshl_add_u64 v[4:5], v[6:7], 0, v[4:5]
	global_store_dword v[4:5], v8, off

.LBB0_238:
	s_or_b64 exec, exec, s[2:3]
	v_lshlrev_b32_e32 v29, 3, v23
	v_lshl_add_u32 v8, v21, 2, v28
	v_mov_b32_e32 v21, v20
	v_mad_u32_u24 v30, v18, s14, v8
	ds_read_b32 v80, v30
	ds_read_b32 v81, v30 offset:260
	ds_read_b32 v82, v30 offset:520
	ds_read_b32 v83, v30 offset:780
	ds_read_b32 v84, v30 offset:1040
	ds_read_b32 v85, v30 offset:1300
	ds_read_b32 v86, v30 offset:1560
	ds_read_b32 v87, v30 offset:1820
	ds_read_b32 v88, v30 offset:2080
	ds_read_b32 v89, v30 offset:2340
	ds_read_b32 v90, v30 offset:2600
	ds_read_b32 v91, v30 offset:2860
	ds_read_b32 v92, v30 offset:3120
	ds_read_b32 v93, v30 offset:3380
	ds_read_b32 v94, v30 offset:3640
	ds_read_b32 v95, v30 offset:3900
	s_waitcnt lgkmcnt(0)
	v_add_f32_e32 v80, v20, v80
	v_add_f32_e32 v81, v20, v81
	v_add_f32_e32 v82, v20, v82
	v_add_f32_e32 v83, v20, v83
	v_add_f32_e32 v84, v20, v84
	v_add_f32_e32 v85, v20, v85
	v_add_f32_e32 v86, v20, v86
	v_add_f32_e32 v87, v20, v87
	v_add_f32_e32 v88, v20, v88
	v_add_f32_e32 v89, v20, v89
	v_add_f32_e32 v90, v20, v90
	v_add_f32_e32 v91, v20, v91
	v_add_f32_e32 v92, v20, v92
	v_add_f32_e32 v93, v20, v93
	v_add_f32_e32 v94, v20, v94
	v_add_f32_e32 v95, v20, v95
	ds_write_b32 v30, v80
	ds_write_b32 v30, v81 offset:260
	ds_write_b32 v30, v82 offset:520
	ds_write_b32 v30, v83 offset:780
	ds_write_b32 v30, v84 offset:1040
	ds_write_b32 v30, v85 offset:1300
	ds_write_b32 v30, v86 offset:1560
	ds_write_b32 v30, v87 offset:1820
	ds_write_b32 v30, v88 offset:2080
	ds_write_b32 v30, v89 offset:2340
	ds_write_b32 v30, v90 offset:2600
	ds_write_b32 v30, v91 offset:2860
	ds_write_b32 v30, v92 offset:3120
	ds_write_b32 v30, v93 offset:3380
	ds_write_b32 v30, v94 offset:3640
	ds_write_b32 v30, v95 offset:3900
	v_and_b32_e32 v9, 63, v22
	v_lshlrev_b32_e32 v10, 2, v9
	v_add_u32_e32 v8, v28, v10
	s_waitcnt lgkmcnt(0)
	s_barrier
	ds_read_b32 v8, v8 offset:16380
	s_movk_i32 s2, 0x90
	v_mad_u32_u24 v9, v9, s2, v28
	v_lshlrev_b32_e32 v11, 5, v17
	s_mov_b32 s2, 0xac00
	v_add3_u32 v9, v9, v11, s2
	v_mul_u32_u24_e32 v11, 0x1040, v17
	v_add3_u32 v10, v28, v11, v10
	v_add_u32_e32 v72, 0x410, v10
	v_add_u32_e32 v73, 0x820, v10
	v_add_u32_e32 v74, 0xc30, v10
	v_add_u32_e32 v76, 0x4400, v10
	v_add_u32_e32 v77, 0x4810, v10
	v_add_u32_e32 v78, 0x4c20, v10
	v_add_u32_e32 v79, 0x5030, v10
	ds_read2_b32 v[96:97], v76 offset1:65
	ds_read2_b32 v[98:99], v10 offset1:65
	ds_read2_b32 v[100:101], v76 offset0:130 offset1:195
	ds_read2_b32 v[102:103], v10 offset0:130 offset1:195
	ds_read2_b32 v[104:105], v77 offset1:65
	ds_read2_b32 v[106:107], v72 offset1:65
	ds_read2_b32 v[108:109], v77 offset0:130 offset1:195
	ds_read2_b32 v[110:111], v72 offset0:130 offset1:195
	ds_read2_b32 v[112:113], v78 offset1:65
	ds_read2_b32 v[114:115], v73 offset1:65
	ds_read2_b32 v[116:117], v78 offset0:130 offset1:195
	ds_read2_b32 v[118:119], v73 offset0:130 offset1:195
	ds_read2_b32 v[120:121], v79 offset1:65
	ds_read2_b32 v[122:123], v74 offset1:65
	ds_read2_b32 v[124:125], v79 offset0:130 offset1:195
	ds_read2_b32 v[126:127], v74 offset0:130 offset1:195
	s_waitcnt lgkmcnt(0)
	v_sub_f32_e32 v98, v8, v98
	v_sub_f32_e32 v99, v8, v99
	v_sub_f32_e32 v102, v8, v102
	v_sub_f32_e32 v103, v8, v103
	s_nop 0
	s_nop 0
	s_nop 0
	s_nop 0
	v_exp_f32_e32 v98, v98
	v_exp_f32_e32 v99, v99
	v_exp_f32_e32 v102, v102
	v_exp_f32_e32 v103, v103
	s_nop 0
	v_mul_f32_e32 v98, v96, v98
	v_mul_f32_e32 v99, v97, v99
	v_mul_f32_e32 v102, v100, v102
	v_mul_f32_e32 v103, v101, v103
	v_cvt_pk_bf16_f32 v96, v98, v99
	v_cvt_pk_bf16_f32 v97, v102, v103
	ds_write_b64 v9, v[96:97]
	v_sub_f32_e32 v106, v8, v106
	v_sub_f32_e32 v107, v8, v107
	v_sub_f32_e32 v110, v8, v110
	v_sub_f32_e32 v111, v8, v111
	s_nop 0
	s_nop 0
	s_nop 0
	s_nop 0
	v_exp_f32_e32 v106, v106
	v_exp_f32_e32 v107, v107
	v_exp_f32_e32 v110, v110
	v_exp_f32_e32 v111, v111
	s_nop 0
	v_mul_f32_e32 v106, v104, v106
	v_mul_f32_e32 v107, v105, v107
	v_mul_f32_e32 v110, v108, v110
	v_mul_f32_e32 v111, v109, v111
	v_cvt_pk_bf16_f32 v104, v106, v107
	v_cvt_pk_bf16_f32 v105, v110, v111
	ds_write_b64 v9, v[104:105] offset:8
	v_sub_f32_e32 v114, v8, v114
	v_sub_f32_e32 v115, v8, v115
	v_sub_f32_e32 v118, v8, v118
	v_sub_f32_e32 v119, v8, v119
	s_nop 0
	s_nop 0
	s_nop 0
	s_nop 0
	v_exp_f32_e32 v114, v114
	v_exp_f32_e32 v115, v115
	v_exp_f32_e32 v118, v118
	v_exp_f32_e32 v119, v119
	s_nop 0
	v_mul_f32_e32 v114, v112, v114
	v_mul_f32_e32 v115, v113, v115
	v_mul_f32_e32 v118, v116, v118
	v_mul_f32_e32 v119, v117, v119
	v_cvt_pk_bf16_f32 v112, v114, v115
	v_cvt_pk_bf16_f32 v113, v118, v119
	ds_write_b64 v9, v[112:113] offset:16
	v_sub_f32_e32 v122, v8, v122
	v_sub_f32_e32 v123, v8, v123
	v_sub_f32_e32 v126, v8, v126
	v_sub_f32_e32 v127, v8, v127
	s_nop 0
	s_nop 0
	s_nop 0
	s_nop 0
	v_exp_f32_e32 v122, v122
	v_exp_f32_e32 v123, v123
	v_exp_f32_e32 v126, v126
	v_exp_f32_e32 v127, v127
	s_nop 0
	v_mul_f32_e32 v122, v120, v122
	v_mul_f32_e32 v123, v121, v123
	v_mul_f32_e32 v126, v124, v126
	v_mul_f32_e32 v127, v125, v127
	v_cvt_pk_bf16_f32 v120, v122, v123
	v_cvt_pk_bf16_f32 v121, v126, v127
	ds_write_b64 v9, v[120:121] offset:24
	v_lshl_add_u32 v12, v29, 1, v28
	s_movk_i32 s2, 0x90
	v_mad_u32_u24 v17, v19, s2, v12
	s_waitcnt lgkmcnt(0)
	s_barrier
	v_readfirstlane_b32 s100, v206
	s_nop 3
	s_lshr_b32 s100, s100, 6
	s_sub_i32 s101, 7, s100
	s_cmp_lt_u32 s100, 4
	s_cselect_b32 s100, s100, s101
	s_cmp_ge_u32 s100, 2
	s_cbranch_scc1 .Llprio_h
	s_setprio 2
.Llprio_h:
	ds_read_b128 v[8:11], v17 offset:34816
	v_mad_u32_u24 v18, v26, s2, v12
	ds_read_b128 v[12:15], v18 offset:44032
	ds_read_b128 v[34:37], v18 offset:46336
	ds_read_b128 v[38:41], v18 offset:48640
	ds_read_b128 v[42:45], v18 offset:50944
	s_waitcnt lgkmcnt(3)
	v_mfma_f32_16x16x32_bf16 v[12:15], v[12:15], v[8:11], 0
	v_lshlrev_b32_e32 v30, 2, v23
	v_mov_b32_e32 v33, v177
	v_or_b32_e32 v51, 16, v26
	s_waitcnt lgkmcnt(2)
	v_mfma_f32_16x16x32_bf16 v[34:37], v[34:37], v[8:11], 0
	v_or_b32_e32 v48, 32, v26
	v_or_b32_e32 v31, 48, v26
	v_cmp_lt_u32_sdwa s[4:5], v22, v216 src0_sel:BYTE_0 src1_sel:DWORD
	s_waitcnt lgkmcnt(1)
	v_mfma_f32_16x16x32_bf16 v[38:41], v[38:41], v[8:11], 0
	s_waitcnt lgkmcnt(0)
	v_mfma_f32_16x16x32_bf16 v[8:11], v[42:45], v[8:11], 0
	ds_read_b128 v[42:45], v17 offset:34880
	ds_read_b128 v[52:55], v18 offset:44096
	v_ashrrev_i32_e32 v17, 31, v16
	v_lshlrev_b64 v[20:21], 14, v[16:17]
	s_waitcnt lgkmcnt(0)
	v_mfma_f32_16x16x32_bf16 v[12:15], v[52:55], v[42:45], v[12:15]
	ds_read_b128 v[52:55], v18 offset:46400
	v_lshl_add_u64 v[20:21], s[78:79], 0, v[20:21]
	s_waitcnt lgkmcnt(0)
	v_mfma_f32_16x16x32_bf16 v[34:37], v[52:55], v[42:45], v[34:37]
	ds_read_b128 v[52:55], v18 offset:48704
	s_waitcnt lgkmcnt(0)
	v_mfma_f32_16x16x32_bf16 v[38:41], v[52:55], v[42:45], v[38:41]
	ds_read_b128 v[52:55], v18 offset:51008
	v_or_b32_e32 v66, v32, v26
	v_lshl_or_b32 v66, v66, 6, v30
	v_lshlrev_b32_e32 v66, 2, v66
	v_mov_b32_e32 v67, v177
	v_lshl_add_u64 v[66:67], v[20:21], 0, v[66:67]
	v_or_b32_e32 v18, v32, v30
	v_lshlrev_b32_e32 v18, 6, v18
	v_or_b32_e32 v23, v18, v26
	v_lshlrev_b32_e32 v32, 2, v23
	v_lshl_add_u64 v[32:33], v[20:21], 0, v[32:33]
	global_store_dwordx4 v[66:67], v[12:15], off sc1
	global_store_dwordx4 v[66:67], v[34:37], off offset:64 sc1
	global_store_dwordx4 v[66:67], v[38:41], off offset:128 sc1
	s_nop 1
	v_or_b32_e32 v12, v18, v51
	v_lshlrev_b32_e32 v12, 2, v12
	v_mov_b32_e32 v13, v177
	v_lshl_add_u64 v[12:13], v[20:21], 0, v[12:13]
	v_or_b32_e32 v12, v18, v48
	v_lshlrev_b32_e32 v12, 2, v12
	v_mov_b32_e32 v13, v177
	s_waitcnt lgkmcnt(0)
	v_mfma_f32_16x16x32_bf16 v[8:11], v[52:55], v[42:45], v[8:11]
	v_lshl_add_u64 v[12:13], v[20:21], 0, v[12:13]
	s_nop 3
	s_nop 3
	global_store_dwordx4 v[66:67], v[8:11], off offset:192 sc1
	s_nop 1
	v_or_b32_e32 v8, v18, v31
	v_lshlrev_b32_e32 v12, 2, v8
	v_mov_b32_e32 v13, v177
	v_lshl_add_u64 v[12:13], v[20:21], 0, v[12:13]
	s_and_saveexec_b64 s[2:3], s[4:5]
	s_cbranch_execz .LBB0_244
	v_lshlrev_b32_sdwa v8, v213, v22 dst_sel:DWORD dst_unused:UNUSED_PAD src0_sel:DWORD src1_sel:BYTE_0
	v_add_u32_e32 v9, v28, v8
	ds_read_b32 v9, v9 offset:16380
	v_readlane_b32 s4, v254, 21
	v_lshlrev_b64 v[10:11], 8, v[16:17]
	v_readlane_b32 s5, v254, 22
	s_waitcnt lgkmcnt(0)
	s_nop 0
	v_exp_f32_e32 v12, v9
	v_lshl_add_u64 v[10:11], s[4:5], 0, v[10:11]
	v_mov_b32_e32 v9, v177
	v_lshl_add_u64 v[8:9], v[10:11], 0, v[8:9]
	global_store_dword v[8:9], v12, off
